# v14 + grid barrier: XCD leader releases local workgroups before its own L1 invalidate
# speedup vs baseline: 1.0017x; 1.0017x over previous
.LBB0_101:
	s_or_b64 exec, exec, s[2:3]
	s_mov_b64 s[2:3], exec
	v_mbcnt_lo_u32_b32 v1, s2, 0
	v_mbcnt_hi_u32_b32 v1, s3, v1
	v_cmp_eq_u32_e32 vcc, 0, v1
	s_waitcnt vmcnt(0)
	s_and_saveexec_b64 s[6:7], vcc
	s_cbranch_execz .LBB0_103
	s_bcnt1_i32_b64 s2, s[2:3]
	v_mov_b32_e32 v1, 0
	v_mov_b32_e32 v2, s2
	global_atomic_add v1, v2, s[4:5]
.LBB0_103:
	s_or_b64 exec, exec, s[6:7]
	buffer_inv sc1
	s_waitcnt vmcnt(0)

.LBB0_1852:
	s_or_b64 exec, exec, s[2:3]
	s_mov_b64 s[2:3], exec
	v_mbcnt_lo_u32_b32 v0, s2, 0
	v_mbcnt_hi_u32_b32 v0, s3, v0
	v_cmp_eq_u32_e32 vcc, 0, v0
	s_waitcnt vmcnt(0)
	s_and_saveexec_b64 s[6:7], vcc
	s_cbranch_execz .LBB0_1854
	s_bcnt1_i32_b64 s2, s[2:3]
	v_mov_b32_e32 v0, 0
	v_mov_b32_e32 v1, s2
	global_atomic_add v0, v1, s[4:5]
